# idxpipe plus indexer half-prologue loads hoisted to the loop top (second cs half, head weights, key tiles 0/1 prefetched into idle registers)
# baseline (speedup 1.0000x reference)
.Lidxd_p:
	v_mad_i64_i32 v[4:5], s[74:75], v2, s80, v[42:43]
	v_lshl_add_u64 v[4:5], v[4:5], 0, v[0:1]
	v_mov_b32_e32 v87, v1
	v_lshl_add_u64 v[4:5], v[4:5], 0, v[86:87]
	s_mov_b64 s[74:75], 0x1200
	v_lshl_add_u64 v[34:35], v[4:5], 0, s[74:75]
	v_add_co_u32_e32 v4, vcc, 0x1000, v4
	global_load_dwordx4 v[10:13], v[34:35], off offset:64
	s_nop 0
	v_addc_co_u32_e32 v5, vcc, 0, v5, vcc
	global_load_dwordx4 v[14:17], v[4:5], off offset:512
	v_ashrrev_i32_e32 v3, 31, v2
	v_lshlrev_b64 v[2:3], 8, v[2:3]
	v_lshl_add_u64 v[44:45], v[82:83], 0, v[2:3]
	global_load_dwordx4 v[18:21], v[44:45], off
	global_load_dwordx4 v[22:25], v[44:45], off offset:16
	global_load_dwordx4 v[26:29], v[44:45], off offset:32
	global_load_dwordx4 v[30:33], v[44:45], off offset:48
	global_load_dwordx4 v[6:9], v[34:35], off offset:32
	global_load_dwordx4 v[2:5], v[34:35], off offset:96
	s_movk_i32 s2, 0xf800
	v_and_b32_e32 v177, 0x7fe, v88
	global_load_dwordx4 v[232:235], v[44:45], off offset:128
	global_load_dwordx4 v[236:239], v[44:45], off offset:144
	global_load_dwordx4 v[240:243], v[44:45], off offset:160
	global_load_dwordx4 v[244:247], v[44:45], off offset:176
	v_or_b32_e32 v184, v88, v94
	v_and_or_b32 v186, v88, s2, v93
	v_mad_i64_i32 v[184:185], vcc, v184, s80, v[42:43]
	v_mad_i64_i32 v[186:187], vcc, v186, s80, v[42:43]
	v_add_co_u32_e32 v184, vcc, 0x3300, v184
	s_nop 1
	v_addc_co_u32_e32 v185, vcc, 0, v185, vcc
	global_load_dwordx4 v[66:69], v[184:185], off
	global_load_dwordx4 v[180:183], v[184:185], off offset:16
	v_lshl_add_u64 v[186:187], v[186:187], 0, v[86:87]
	v_add_co_u32_e32 v186, vcc, 0x3200, v186
	s_nop 1
	v_addc_co_u32_e32 v187, vcc, 0, v187, vcc
	global_load_dwordx4 v[216:219], v[186:187], off
	global_load_dwordx4 v[220:223], v[186:187], off offset:32
	global_load_dwordx4 v[224:227], v[186:187], off offset:64
	global_load_dwordx4 v[228:231], v[186:187], off offset:96
	v_add_co_u32_e32 v188, vcc, 0x68000, v186
	s_nop 1
	v_addc_co_u32_e32 v189, vcc, 0, v187, vcc
	global_load_dwordx4 v[58:61], v[188:189], off
	global_load_dwordx4 v[54:57], v[188:189], off offset:32
	global_load_dwordx4 v[50:53], v[188:189], off offset:64
	global_load_dwordx4 v[62:65], v[188:189], off offset:96
	s_waitcnt vmcnt(7)
	v_lshlrev_b32_e32 v34, 16, v10
	v_and_b32_e32 v10, 0xffff0000, v10
	v_lshlrev_b32_e32 v36, 16, v11
	v_and_b32_e32 v38, 0xffff0000, v11
	v_lshlrev_b32_e32 v40, 16, v12
	v_and_b32_e32 v12, 0xffff0000, v12
	v_lshlrev_b32_e32 v46, 16, v13
	v_and_b32_e32 v48, 0xffff0000, v13
	s_waitcnt vmcnt(6)
	v_lshlrev_b32_e32 v35, 16, v14
	v_and_b32_e32 v11, 0xffff0000, v14
	v_lshlrev_b32_e32 v37, 16, v15
	v_and_b32_e32 v39, 0xffff0000, v15
	v_lshlrev_b32_e32 v41, 16, v16
	v_and_b32_e32 v13, 0xffff0000, v16
	v_lshlrev_b32_e32 v47, 16, v17
	v_and_b32_e32 v49, 0xffff0000, v17
	s_waitcnt vmcnt(5)
	v_pk_mul_f32 v[14:15], v[18:19], v[34:35] op_sel:[0,1] op_sel_hi:[1,0]
	v_pk_mul_f32 v[16:17], v[18:19], v[34:35]
	v_pk_mul_f32 v[18:19], v[20:21], v[10:11] op_sel:[0,1] op_sel_hi:[1,0]
	v_pk_mul_f32 v[10:11], v[20:21], v[10:11]
	s_waitcnt vmcnt(4)
	v_pk_mul_f32 v[20:21], v[22:23], v[36:37] op_sel:[0,1] op_sel_hi:[1,0]
	v_pk_mul_f32 v[22:23], v[22:23], v[36:37]
	v_pk_mul_f32 v[34:35], v[24:25], v[38:39] op_sel:[0,1] op_sel_hi:[1,0]
	v_pk_mul_f32 v[24:25], v[24:25], v[38:39]
	s_waitcnt vmcnt(3)
	v_pk_mul_f32 v[36:37], v[26:27], v[40:41] op_sel:[0,1] op_sel_hi:[1,0]
	v_pk_mul_f32 v[26:27], v[26:27], v[40:41]
	v_pk_mul_f32 v[38:39], v[28:29], v[12:13] op_sel:[0,1] op_sel_hi:[1,0]
	v_pk_mul_f32 v[12:13], v[28:29], v[12:13]
	s_waitcnt vmcnt(2)
	v_pk_mul_f32 v[28:29], v[30:31], v[46:47] op_sel:[0,1] op_sel_hi:[1,0]
	v_pk_mul_f32 v[30:31], v[30:31], v[46:47]
	v_pk_mul_f32 v[40:41], v[32:33], v[48:49] op_sel:[0,1] op_sel_hi:[1,0]
	v_pk_mul_f32 v[32:33], v[32:33], v[48:49]
	v_sub_f32_e32 v14, v14, v15
	v_add_f32_e32 v15, v17, v16
	v_sub_f32_e32 v16, v18, v19
	v_add_f32_e32 v10, v10, v11
	v_sub_f32_e32 v11, v20, v21
	v_add_f32_e32 v17, v22, v23
	v_sub_f32_e32 v18, v34, v35
	v_add_f32_e32 v19, v24, v25
	v_sub_f32_e32 v20, v36, v37
	v_add_f32_e32 v21, v26, v27
	v_sub_f32_e32 v22, v38, v39
	v_add_f32_e32 v12, v12, v13
	v_sub_f32_e32 v13, v28, v29
	v_add_f32_e32 v23, v30, v31
	v_sub_f32_e32 v24, v40, v41
	v_add_f32_e32 v25, v32, v33
	v_cvt_pk_bf16_f32 v38, v14, v16
	v_cvt_pk_bf16_f32 v39, v11, v18
	v_cvt_pk_bf16_f32 v40, v20, v22
	v_cvt_pk_bf16_f32 v41, v13, v24
	v_cvt_pk_bf16_f32 v34, v15, v10
	v_cvt_pk_bf16_f32 v35, v17, v19
	v_cvt_pk_bf16_f32 v36, v21, v12
	v_cvt_pk_bf16_f32 v37, v23, v25
	s_waitcnt vmcnt(0)
	v_mov_b64_e32 v[10:11], v[232:233]
	v_mov_b64_e32 v[12:13], v[234:235]
	v_mov_b64_e32 v[14:15], v[236:237]
	v_mov_b64_e32 v[16:17], v[238:239]
	v_mov_b64_e32 v[18:19], v[240:241]
	v_mov_b64_e32 v[20:21], v[242:243]
	v_mov_b64_e32 v[22:23], v[244:245]
	v_mov_b64_e32 v[24:25], v[246:247]
	v_or_b32_e32 v26, v88, v94
	v_and_or_b32 v28, v88, s2, v93
	v_mad_i64_i32 v[26:27], s[74:75], v26, s80, v[42:43]
	s_movk_i32 s2, 0x3000
	v_mad_i64_i32 v[28:29], s[74:75], v28, s80, v[42:43]
	v_add_co_u32_e32 v32, vcc, s2, v26
	v_lshl_add_u64 v[30:31], v[28:29], 0, v[86:87]
	s_nop 0
	v_addc_co_u32_e32 v33, vcc, 0, v27, vcc
	s_waitcnt vmcnt(5)
	v_lshlrev_b32_e32 v27, 16, v6
	v_and_b32_e32 v29, 0xffff0000, v6
	v_lshlrev_b32_e32 v43, 16, v7
	v_and_b32_e32 v7, 0xffff0000, v7
	v_lshlrev_b32_e32 v45, 16, v8
	v_and_b32_e32 v47, 0xffff0000, v8
	v_lshlrev_b32_e32 v49, 16, v9
	v_and_b32_e32 v9, 0xffff0000, v9
	s_waitcnt vmcnt(4)
	v_lshlrev_b32_e32 v26, 16, v2
	v_and_b32_e32 v28, 0xffff0000, v2
	v_lshlrev_b32_e32 v42, 16, v3
	v_and_b32_e32 v6, 0xffff0000, v3
	v_lshlrev_b32_e32 v44, 16, v4
	v_and_b32_e32 v46, 0xffff0000, v4
	v_and_b32_e32 v8, 0xffff0000, v5
	s_mov_b64 s[74:75], 0x3200
	v_lshlrev_b32_e32 v48, 16, v5
	v_lshl_add_u64 v[90:91], v[30:31], 0, s[74:75]
	v_add_co_u32_e32 v30, vcc, 0x3000, v30
	v_cmp_lt_u32_e64 s[74:75], 31, v177
	s_nop 0
	v_addc_co_u32_e32 v31, vcc, 0, v31, vcc
	s_waitcnt vmcnt(3)
	v_pk_mul_f32 v[2:3], v[10:11], v[26:27] op_sel:[0,1] op_sel_hi:[1,0]
	v_pk_mul_f32 v[4:5], v[10:11], v[26:27]
	v_pk_mul_f32 v[10:11], v[12:13], v[28:29] op_sel:[0,1] op_sel_hi:[1,0]
	v_pk_mul_f32 v[12:13], v[12:13], v[28:29]
	s_waitcnt vmcnt(2)
	v_pk_mul_f32 v[26:27], v[14:15], v[42:43] op_sel:[0,1] op_sel_hi:[1,0]
	v_pk_mul_f32 v[14:15], v[14:15], v[42:43]
	v_pk_mul_f32 v[28:29], v[16:17], v[6:7] op_sel:[0,1] op_sel_hi:[1,0]
	v_pk_mul_f32 v[6:7], v[16:17], v[6:7]
	s_waitcnt vmcnt(1)
	v_pk_mul_f32 v[16:17], v[18:19], v[44:45] op_sel:[0,1] op_sel_hi:[1,0]
	v_pk_mul_f32 v[18:19], v[18:19], v[44:45]
	v_pk_mul_f32 v[42:43], v[20:21], v[46:47] op_sel:[0,1] op_sel_hi:[1,0]
	v_pk_mul_f32 v[20:21], v[20:21], v[46:47]
	s_waitcnt vmcnt(0)
	v_pk_mul_f32 v[46:47], v[24:25], v[8:9] op_sel:[0,1] op_sel_hi:[1,0]
	v_pk_mul_f32 v[44:45], v[22:23], v[48:49] op_sel:[0,1] op_sel_hi:[1,0]
	v_pk_mul_f32 v[22:23], v[22:23], v[48:49]
	v_pk_mul_f32 v[8:9], v[24:25], v[8:9]
	v_sub_f32_e32 v2, v2, v3
	v_add_f32_e32 v3, v4, v5
	v_sub_f32_e32 v4, v10, v11
	v_add_f32_e32 v5, v12, v13
	v_add_f32_e32 v13, v18, v19
	v_sub_f32_e32 v18, v46, v47
	v_sub_f32_e32 v10, v26, v27
	v_add_f32_e32 v11, v14, v15
	v_sub_f32_e32 v12, v28, v29
	v_add_f32_e32 v6, v6, v7
	v_sub_f32_e32 v7, v16, v17
	v_sub_f32_e32 v14, v42, v43
	v_add_f32_e32 v15, v20, v21
	v_sub_f32_e32 v16, v44, v45
	v_add_f32_e32 v17, v22, v23
	v_add_f32_e32 v8, v8, v9
	v_cvt_pk_bf16_f32 v46, v2, v4
	v_cvt_pk_bf16_f32 v47, v10, v12
	v_cvt_pk_bf16_f32 v48, v7, v14
	v_cvt_pk_bf16_f32 v49, v16, v18
	v_cvt_pk_bf16_f32 v42, v3, v5
	v_cvt_pk_bf16_f32 v43, v11, v6
	v_cvt_pk_bf16_f32 v44, v13, v15
	v_cvt_pk_bf16_f32 v45, v17, v8
	s_waitcnt vmcnt(0)
	v_mov_b64_e32 v[26:27], v[220:221]
	v_mov_b64_e32 v[28:29], v[222:223]
	v_mov_b64_e32 v[18:19], v[224:225]
	v_mov_b64_e32 v[20:21], v[226:227]
	v_mov_b64_e32 v[2:3], v[66:67]
	v_mov_b64_e32 v[4:5], v[68:69]
	v_mov_b64_e32 v[22:23], v[228:229]
	v_mov_b64_e32 v[24:25], v[230:231]
	v_mov_b64_e32 v[6:7], v[216:217]
	v_mov_b64_e32 v[8:9], v[218:219]
	v_mov_b64_e32 v[10:11], v[180:181]
	v_mov_b64_e32 v[12:13], v[182:183]
	v_lshlrev_b32_e32 v174, 16, v2
	s_waitcnt vmcnt(0)
	v_lshlrev_b32_e32 v166, 16, v10
	v_and_b32_e32 v173, 0xffff0000, v2
	v_and_b32_e32 v165, 0xffff0000, v10
	v_lshlrev_b32_e32 v172, 16, v3
	v_lshlrev_b32_e32 v164, 16, v11
	v_and_b32_e32 v171, 0xffff0000, v3
	v_and_b32_e32 v163, 0xffff0000, v11
	v_lshlrev_b32_e32 v170, 16, v4
	v_lshlrev_b32_e32 v162, 16, v12
	v_and_b32_e32 v169, 0xffff0000, v4
	v_and_b32_e32 v161, 0xffff0000, v12
	v_lshlrev_b32_e32 v168, 16, v5
	v_lshlrev_b32_e32 v160, 16, v13
	v_and_b32_e32 v167, 0xffff0000, v5
	v_and_b32_e32 v89, 0xffff0000, v13
	v_mfma_f32_32x32x16_bf16 v[2:17], v[38:41], v[6:9], 0
	v_or_b32_e32 v87, v177, v94
	v_mov_b32_e32 v175, 0
	v_mfma_f32_32x32x16_bf16 v[2:17], v[46:49], v[26:29], v[2:17]
	v_mfma_f32_32x32x16_bf16 v[2:17], v[34:37], v[18:21], v[2:17]
	v_mfma_f32_32x32x16_bf16 v[2:17], v[42:45], v[22:25], v[2:17]
	s_and_saveexec_b64 s[80:81], s[74:75]
	s_cbranch_execz .Lidxp_e1
	s_waitcnt lgkmcnt(0)
	s_waitcnt vmcnt(0)
	s_barrier
	v_mfma_f32_32x32x16_bf16 v[18:33], v[38:41], v[58:61], 0
	v_mfma_f32_32x32x16_bf16 v[18:33], v[46:49], v[54:57], v[18:33]
	v_mfma_f32_32x32x16_bf16 v[18:33], v[34:37], v[50:53], v[18:33]
	v_mfma_f32_32x32x16_bf16 v[18:33], v[42:45], v[62:65], v[18:33]
	ds_read_b128 v[58:61], v74 offset:0
	ds_read_b128 v[54:57], v75 offset:0
	ds_read_b128 v[50:53], v76 offset:0
	ds_read_b128 v[62:65], v77 offset:0
	v_max_f32_e32 v2, 0, v2
	v_fma_f32 v2, v174, v2, 0
	v_max_f32_e32 v3, 0, v3
	v_fmac_f32_e32 v2, v173, v3
	v_max_f32_e32 v3, 0, v4
	v_fmac_f32_e32 v2, v172, v3
	v_max_f32_e32 v3, 0, v5
	v_fmac_f32_e32 v2, v171, v3
	v_max_f32_e32 v3, 0, v6
	v_fmac_f32_e32 v2, v170, v3
	v_max_f32_e32 v3, 0, v7
	v_fmac_f32_e32 v2, v169, v3
	v_max_f32_e32 v3, 0, v8
	v_fmac_f32_e32 v2, v168, v3
	v_max_f32_e32 v3, 0, v9
	v_fmac_f32_e32 v2, v167, v3
	v_max_f32_e32 v3, 0, v10
	v_fmac_f32_e32 v2, v166, v3
	v_max_f32_e32 v3, 0, v11
	v_fmac_f32_e32 v2, v165, v3
	v_max_f32_e32 v3, 0, v12
	v_fmac_f32_e32 v2, v164, v3
	v_max_f32_e32 v3, 0, v13
	v_fmac_f32_e32 v2, v163, v3
	v_max_f32_e32 v3, 0, v14
	v_fmac_f32_e32 v2, v162, v3
	v_max_f32_e32 v3, 0, v15
	v_fmac_f32_e32 v2, v161, v3
	v_max_f32_e32 v3, 0, v16
	v_fmac_f32_e32 v2, v160, v3
	v_max_f32_e32 v3, 0, v17
	v_fmac_f32_e32 v2, v89, v3
	v_not_b32_e32 v3, v2
	v_or_b32_e32 v4, 0x80000000, v2
	v_cmp_gt_i32_e32 vcc, 0, v2
	s_nop 1
	v_cndmask_b32_e32 v2, v4, v3, vcc
	v_cmp_le_u32_e32 vcc, v93, v87
	s_nop 1
	v_cndmask_b32_e32 v81, 0, v2, vcc
